# prologue weight transposes with per-k gain: 64 row loads issued together, gains via one vector load + readlane (was one load+wait per row)
# speedup vs baseline: 1.0329x; 1.0147x over previous
; #define LDS_WAIT() asm volatile("s_waitcnt lgkmcnt(0)" ::: "memory")
; template <int MAP> __device__ __forceinline__ void transpose_item(const float* W, int K, int N, const float* gk, bf16_t* WT, LAS float* scr, int item, int lane) {
;     ...
;     const int nn = n0 + lane; const bool okn = nn < N;
; #pragma unroll
;     for (int i = 0; i < 64; ++i) { float v = okn ? W[(size_t)(k0 + i) * N + nn] : 0.f; if (gk) v *= gk[k0 + i]; scr[i * 65 + lane] = v; }
;     LDS_WAIT();
.LBB0_25:
	s_andn2_b64 vcc, exec, s[4:5]
	s_cbranch_vccnz .LBB0_155
	s_mul_i32 s5, s78, 0xb00000
	s_mul_hi_i32 s4, s78, 0xb00000
	s_add_u32 s6, s58, s5
	s_addc_u32 s7, s59, s4
	s_lshl_b32 s4, s78, 10
	s_ashr_i32 s5, s4, 31
	s_lshl_b64 s[4:5], s[4:5], 2
	s_add_u32 s8, s54, s4
	s_addc_u32 s9, s55, s5
	s_add_i32 s4, s80, 0xf950
	s_and_b32 s5, s4, 0xffff
	s_mul_i32 s5, s5, 0xba2f
	s_lshr_b32 s10, s5, 21
	s_mul_i32 s10, s10, 44
	s_sub_i32 s4, s4, s10
	s_lshr_b32 s5, s5, 15
	s_lshl_b32 s4, s4, 6
	s_and_b32 s10, s5, 0xffc0
	s_and_b32 s11, s4, 0xffc0
	v_or_b32_e32 v2, s11, v1
	s_mul_i32 s12, s10, 0xb00
	v_or_b32_e32 v3, s12, v2
	v_lshlrev_b32_e32 v3, 2, v3
	v_mov_b32_e32 v214, 1.0
	s_and_b64 vcc, exec, s[74:75]
	s_cbranch_vccz .Lpro_up_nog
	v_lshlrev_b32_e32 v215, 2, v1
	v_lshl_add_u32 v215, s10, 2, v215
	global_load_dword v214, v215, s[8:9]
.Lpro_up_nog:
	s_movk_i32 s32, 0x2c00
	global_load_dword v150, v3, s[6:7]
	v_add_u32_e32 v3, s32, v3
	global_load_dword v151, v3, s[6:7]
	v_add_u32_e32 v3, s32, v3
	global_load_dword v152, v3, s[6:7]
	v_add_u32_e32 v3, s32, v3
	global_load_dword v153, v3, s[6:7]
	v_add_u32_e32 v3, s32, v3
	global_load_dword v154, v3, s[6:7]
	v_add_u32_e32 v3, s32, v3
	global_load_dword v155, v3, s[6:7]
	v_add_u32_e32 v3, s32, v3
	global_load_dword v156, v3, s[6:7]
	v_add_u32_e32 v3, s32, v3
	global_load_dword v157, v3, s[6:7]
	v_add_u32_e32 v3, s32, v3
	global_load_dword v158, v3, s[6:7]
	v_add_u32_e32 v3, s32, v3
	global_load_dword v159, v3, s[6:7]
	v_add_u32_e32 v3, s32, v3
	global_load_dword v160, v3, s[6:7]
	v_add_u32_e32 v3, s32, v3
	global_load_dword v161, v3, s[6:7]
	v_add_u32_e32 v3, s32, v3
	global_load_dword v162, v3, s[6:7]
	v_add_u32_e32 v3, s32, v3
	global_load_dword v163, v3, s[6:7]
	v_add_u32_e32 v3, s32, v3
	global_load_dword v164, v3, s[6:7]
	v_add_u32_e32 v3, s32, v3
	global_load_dword v165, v3, s[6:7]
	v_add_u32_e32 v3, s32, v3
	global_load_dword v166, v3, s[6:7]
	v_add_u32_e32 v3, s32, v3
	global_load_dword v167, v3, s[6:7]
	v_add_u32_e32 v3, s32, v3
	global_load_dword v168, v3, s[6:7]
	v_add_u32_e32 v3, s32, v3
	global_load_dword v169, v3, s[6:7]
	v_add_u32_e32 v3, s32, v3
	global_load_dword v170, v3, s[6:7]
	v_add_u32_e32 v3, s32, v3
	global_load_dword v171, v3, s[6:7]
	v_add_u32_e32 v3, s32, v3
	global_load_dword v172, v3, s[6:7]
	v_add_u32_e32 v3, s32, v3
	global_load_dword v173, v3, s[6:7]
	v_add_u32_e32 v3, s32, v3
	global_load_dword v174, v3, s[6:7]
	v_add_u32_e32 v3, s32, v3
	global_load_dword v175, v3, s[6:7]
	v_add_u32_e32 v3, s32, v3
	global_load_dword v176, v3, s[6:7]
	v_add_u32_e32 v3, s32, v3
	global_load_dword v177, v3, s[6:7]
	v_add_u32_e32 v3, s32, v3
	global_load_dword v178, v3, s[6:7]
	v_add_u32_e32 v3, s32, v3
	global_load_dword v179, v3, s[6:7]
	v_add_u32_e32 v3, s32, v3
	global_load_dword v180, v3, s[6:7]
	v_add_u32_e32 v3, s32, v3
	global_load_dword v181, v3, s[6:7]
	v_add_u32_e32 v3, s32, v3
	global_load_dword v182, v3, s[6:7]
	v_add_u32_e32 v3, s32, v3
	global_load_dword v183, v3, s[6:7]
	v_add_u32_e32 v3, s32, v3
	global_load_dword v184, v3, s[6:7]
	v_add_u32_e32 v3, s32, v3
	global_load_dword v185, v3, s[6:7]
	v_add_u32_e32 v3, s32, v3
	global_load_dword v186, v3, s[6:7]
	v_add_u32_e32 v3, s32, v3
	global_load_dword v187, v3, s[6:7]
	v_add_u32_e32 v3, s32, v3
	global_load_dword v188, v3, s[6:7]
	v_add_u32_e32 v3, s32, v3
	global_load_dword v189, v3, s[6:7]
	v_add_u32_e32 v3, s32, v3
	global_load_dword v190, v3, s[6:7]
	v_add_u32_e32 v3, s32, v3
	global_load_dword v191, v3, s[6:7]
	v_add_u32_e32 v3, s32, v3
	global_load_dword v192, v3, s[6:7]
	v_add_u32_e32 v3, s32, v3
	global_load_dword v193, v3, s[6:7]
	v_add_u32_e32 v3, s32, v3
	global_load_dword v194, v3, s[6:7]
	v_add_u32_e32 v3, s32, v3
	global_load_dword v195, v3, s[6:7]
	v_add_u32_e32 v3, s32, v3
	global_load_dword v196, v3, s[6:7]
	v_add_u32_e32 v3, s32, v3
	global_load_dword v197, v3, s[6:7]
	v_add_u32_e32 v3, s32, v3
	global_load_dword v198, v3, s[6:7]
	v_add_u32_e32 v3, s32, v3
	global_load_dword v199, v3, s[6:7]
	v_add_u32_e32 v3, s32, v3
	global_load_dword v200, v3, s[6:7]
	v_add_u32_e32 v3, s32, v3
	global_load_dword v201, v3, s[6:7]
	v_add_u32_e32 v3, s32, v3
	global_load_dword v202, v3, s[6:7]
	v_add_u32_e32 v3, s32, v3
	global_load_dword v203, v3, s[6:7]
	v_add_u32_e32 v3, s32, v3
	global_load_dword v204, v3, s[6:7]
	v_add_u32_e32 v3, s32, v3
	global_load_dword v205, v3, s[6:7]
	v_add_u32_e32 v3, s32, v3
	global_load_dword v206, v3, s[6:7]
	v_add_u32_e32 v3, s32, v3
	global_load_dword v207, v3, s[6:7]
	v_add_u32_e32 v3, s32, v3
	global_load_dword v208, v3, s[6:7]
	v_add_u32_e32 v3, s32, v3
	global_load_dword v209, v3, s[6:7]
	v_add_u32_e32 v3, s32, v3
	global_load_dword v210, v3, s[6:7]
	v_add_u32_e32 v3, s32, v3
	global_load_dword v211, v3, s[6:7]
	v_add_u32_e32 v3, s32, v3
	global_load_dword v212, v3, s[6:7]
	v_add_u32_e32 v3, s32, v3
	global_load_dword v213, v3, s[6:7]
	v_add_u32_e32 v3, s32, v3
	s_waitcnt vmcnt(60)
	v_readlane_b32 s98, v214, 0
	v_readlane_b32 s99, v214, 1
	v_readlane_b32 s100, v214, 2
	v_readlane_b32 s101, v214, 3
	v_mul_f32_e32 v150, s98, v150
	v_mul_f32_e32 v151, s99, v151
	v_mul_f32_e32 v152, s100, v152
	v_mul_f32_e32 v153, s101, v153
	ds_write_b32 v68, v150
	ds_write_b32 v68, v151 offset:260
	ds_write_b32 v68, v152 offset:520
	ds_write_b32 v68, v153 offset:780
	s_waitcnt vmcnt(56)
	v_readlane_b32 s98, v214, 4
	v_readlane_b32 s99, v214, 5
	v_readlane_b32 s100, v214, 6
	v_readlane_b32 s101, v214, 7
	v_mul_f32_e32 v154, s98, v154
	v_mul_f32_e32 v155, s99, v155
	v_mul_f32_e32 v156, s100, v156
	v_mul_f32_e32 v157, s101, v157
	ds_write_b32 v68, v154 offset:1040
	ds_write_b32 v68, v155 offset:1300
	ds_write_b32 v68, v156 offset:1560
	ds_write_b32 v68, v157 offset:1820
	s_waitcnt vmcnt(52)
; #define LDS_WAIT() asm volatile("s_waitcnt lgkmcnt(0)" ::: "memory")
; template <int MAP> __device__ __forceinline__ void transpose_item(const float* W, int K, int N, const float* gk, bf16_t* WT, LAS float* scr, int item, int lane) {
;     ...
;     const int nn = n0 + lane; const bool okn = nn < N;
; #pragma unroll
;     for (int i = 0; i < 64; ++i) { float v = okn ? W[(size_t)(k0 + i) * N + nn] : 0.f; if (gk) v *= gk[k0 + i]; scr[i * 65 + lane] = v; }
;     LDS_WAIT();
	v_readlane_b32 s98, v214, 8
	v_readlane_b32 s99, v214, 9
	v_readlane_b32 s100, v214, 10
	v_readlane_b32 s101, v214, 11
	v_mul_f32_e32 v158, s98, v158
	v_mul_f32_e32 v159, s99, v159
	v_mul_f32_e32 v160, s100, v160
	v_mul_f32_e32 v161, s101, v161
	ds_write_b32 v68, v158 offset:2080
	ds_write_b32 v68, v159 offset:2340
	ds_write_b32 v68, v160 offset:2600
	ds_write_b32 v68, v161 offset:2860
	s_waitcnt vmcnt(48)
	v_readlane_b32 s98, v214, 12
	v_readlane_b32 s99, v214, 13
	v_readlane_b32 s100, v214, 14
	v_readlane_b32 s101, v214, 15
	v_mul_f32_e32 v162, s98, v162
	v_mul_f32_e32 v163, s99, v163
	v_mul_f32_e32 v164, s100, v164
	v_mul_f32_e32 v165, s101, v165
	ds_write_b32 v68, v162 offset:3120
	ds_write_b32 v68, v163 offset:3380
	ds_write_b32 v68, v164 offset:3640
	ds_write_b32 v68, v165 offset:3900
	s_waitcnt vmcnt(44)
	v_readlane_b32 s98, v214, 16
	v_readlane_b32 s99, v214, 17
	v_readlane_b32 s100, v214, 18
	v_readlane_b32 s101, v214, 19
	v_mul_f32_e32 v166, s98, v166
	v_mul_f32_e32 v167, s99, v167
	v_mul_f32_e32 v168, s100, v168
	v_mul_f32_e32 v169, s101, v169
	ds_write_b32 v68, v166 offset:4160
	ds_write_b32 v68, v167 offset:4420
	ds_write_b32 v68, v168 offset:4680
	ds_write_b32 v68, v169 offset:4940
	s_waitcnt vmcnt(40)
	v_readlane_b32 s98, v214, 20
	v_readlane_b32 s99, v214, 21
	v_readlane_b32 s100, v214, 22
	v_readlane_b32 s101, v214, 23
	v_mul_f32_e32 v170, s98, v170
	v_mul_f32_e32 v171, s99, v171
	v_mul_f32_e32 v172, s100, v172
	v_mul_f32_e32 v173, s101, v173
	ds_write_b32 v68, v170 offset:5200
	ds_write_b32 v68, v171 offset:5460
	ds_write_b32 v68, v172 offset:5720
	ds_write_b32 v68, v173 offset:5980
	s_waitcnt vmcnt(36)
	v_readlane_b32 s98, v214, 24
	v_readlane_b32 s99, v214, 25
	v_readlane_b32 s100, v214, 26
	v_readlane_b32 s101, v214, 27
	v_mul_f32_e32 v174, s98, v174
	v_mul_f32_e32 v175, s99, v175
	v_mul_f32_e32 v176, s100, v176
	v_mul_f32_e32 v177, s101, v177
	ds_write_b32 v68, v174 offset:6240
	ds_write_b32 v68, v175 offset:6500
	ds_write_b32 v68, v176 offset:6760
	ds_write_b32 v68, v177 offset:7020
	s_waitcnt vmcnt(32)
	v_readlane_b32 s98, v214, 28
	v_readlane_b32 s99, v214, 29
	v_readlane_b32 s100, v214, 30
	v_readlane_b32 s101, v214, 31
	v_mul_f32_e32 v178, s98, v178
	v_mul_f32_e32 v179, s99, v179
	v_mul_f32_e32 v180, s100, v180
	v_mul_f32_e32 v181, s101, v181
	ds_write_b32 v68, v178 offset:7280
	ds_write_b32 v68, v179 offset:7540
	ds_write_b32 v68, v180 offset:7800
	ds_write_b32 v68, v181 offset:8060
	s_waitcnt vmcnt(28)
	v_readlane_b32 s98, v214, 32
	v_readlane_b32 s99, v214, 33
	v_readlane_b32 s100, v214, 34
	v_readlane_b32 s101, v214, 35
	v_mul_f32_e32 v182, s98, v182
	v_mul_f32_e32 v183, s99, v183
	v_mul_f32_e32 v184, s100, v184
	v_mul_f32_e32 v185, s101, v185
	ds_write_b32 v68, v182 offset:8320
	ds_write_b32 v68, v183 offset:8580
	ds_write_b32 v68, v184 offset:8840
	ds_write_b32 v68, v185 offset:9100
	s_waitcnt vmcnt(24)
	v_readlane_b32 s98, v214, 36
	v_readlane_b32 s99, v214, 37
	v_readlane_b32 s100, v214, 38
	v_readlane_b32 s101, v214, 39
	v_mul_f32_e32 v186, s98, v186
	v_mul_f32_e32 v187, s99, v187
	v_mul_f32_e32 v188, s100, v188
	v_mul_f32_e32 v189, s101, v189
	ds_write_b32 v68, v186 offset:9360
	ds_write_b32 v68, v187 offset:9620
	ds_write_b32 v68, v188 offset:9880
	ds_write_b32 v68, v189 offset:10140
	s_waitcnt vmcnt(20)
	v_readlane_b32 s98, v214, 40
	v_readlane_b32 s99, v214, 41
	v_readlane_b32 s100, v214, 42
	v_readlane_b32 s101, v214, 43
	v_mul_f32_e32 v190, s98, v190
	v_mul_f32_e32 v191, s99, v191
	v_mul_f32_e32 v192, s100, v192
	v_mul_f32_e32 v193, s101, v193
	ds_write_b32 v68, v190 offset:10400
	ds_write_b32 v68, v191 offset:10660
	ds_write_b32 v68, v192 offset:10920
	ds_write_b32 v68, v193 offset:11180
	s_waitcnt vmcnt(16)
	v_readlane_b32 s98, v214, 44
	v_readlane_b32 s99, v214, 45
	v_readlane_b32 s100, v214, 46
	v_readlane_b32 s101, v214, 47
	v_mul_f32_e32 v194, s98, v194
	v_mul_f32_e32 v195, s99, v195
	v_mul_f32_e32 v196, s100, v196
	v_mul_f32_e32 v197, s101, v197
	ds_write_b32 v68, v194 offset:11440
	ds_write_b32 v68, v195 offset:11700
	ds_write_b32 v68, v196 offset:11960
	ds_write_b32 v68, v197 offset:12220
	s_waitcnt vmcnt(12)
	v_readlane_b32 s98, v214, 48
	v_readlane_b32 s99, v214, 49
	v_readlane_b32 s100, v214, 50
	v_readlane_b32 s101, v214, 51
	v_mul_f32_e32 v198, s98, v198
	v_mul_f32_e32 v199, s99, v199
	v_mul_f32_e32 v200, s100, v200
	v_mul_f32_e32 v201, s101, v201
	ds_write_b32 v68, v198 offset:12480
	ds_write_b32 v68, v199 offset:12740
	ds_write_b32 v68, v200 offset:13000
	ds_write_b32 v68, v201 offset:13260
	s_waitcnt vmcnt(8)
	v_readlane_b32 s98, v214, 52
	v_readlane_b32 s99, v214, 53
	v_readlane_b32 s100, v214, 54
	v_readlane_b32 s101, v214, 55
	v_mul_f32_e32 v202, s98, v202
	v_mul_f32_e32 v203, s99, v203
	v_mul_f32_e32 v204, s100, v204
	v_mul_f32_e32 v205, s101, v205
	ds_write_b32 v68, v202 offset:13520
	ds_write_b32 v68, v203 offset:13780
	ds_write_b32 v68, v204 offset:14040
	ds_write_b32 v68, v205 offset:14300
	s_waitcnt vmcnt(4)
	v_readlane_b32 s98, v214, 56
	v_readlane_b32 s99, v214, 57
	v_readlane_b32 s100, v214, 58
	v_readlane_b32 s101, v214, 59
	v_mul_f32_e32 v206, s98, v206
	v_mul_f32_e32 v207, s99, v207
	v_mul_f32_e32 v208, s100, v208
	v_mul_f32_e32 v209, s101, v209
	ds_write_b32 v68, v206 offset:14560
	ds_write_b32 v68, v207 offset:14820
	ds_write_b32 v68, v208 offset:15080
	ds_write_b32 v68, v209 offset:15340
	s_waitcnt vmcnt(0)
	v_readlane_b32 s98, v214, 60
	v_readlane_b32 s99, v214, 61
	v_readlane_b32 s100, v214, 62
	v_readlane_b32 s101, v214, 63
	v_mul_f32_e32 v210, s98, v210
	v_mul_f32_e32 v211, s99, v211
	v_mul_f32_e32 v212, s100, v212
	v_mul_f32_e32 v213, s101, v213
	ds_write_b32 v68, v210 offset:15600
	ds_write_b32 v68, v211 offset:15860
	ds_write_b32 v68, v212 offset:16120
	ds_write_b32 v68, v213 offset:16380
	s_add_u32 s4, s97, 0x800000
	s_addc_u32 s5, s71, 0
	s_lshl_b32 s6, s11, 1
	s_waitcnt lgkmcnt(0)
; #define LAS __attribute__((address_space(3)))
; __device__ __forceinline__ unsigned pk2(float lo, float hi) { pk_f32x2_t v = {lo, hi}; pk_bf16x2_t b = __builtin_convertvector(v, pk_bf16x2_t); return __builtin_bit_cast(unsigned, b); }
; #define LDS_WAIT() asm volatile("s_waitcnt lgkmcnt(0)" ::: "memory")
; template <int MAP> __device__ __forceinline__ void transpose_item(const float* W, int K, int N, const float* gk, bf16_t* WT, LAS float* scr, int item, int lane) {
;     ...
;     const int c = lane & 7;
; #pragma unroll
;     for (int j = 0; j < 8; ++j) { const int n = (lane >> 3) + 8 * j; const LAS float* s = scr + (8 * c) * 65 + n;
;         if (n0 + n < N) { u32x4 o; o.x = pk2(s[0 * 65], s[1 * 65]); o.y = pk2(s[2 * 65], s[3 * 65]); o.z = pk2(s[4 * 65], s[5 * 65]); o.w = pk2(s[6 * 65], s[7 * 65]);
;             if (MAP == 4) { const int nn2 = n0 + n, kk2 = k0 + 8 * c; *(u32x4*)(WT + ((size_t)(((nn2 >> 5) * (K >> 4) + (kk2 >> 4)) * 64 + ((kk2 >> 3) & 1) * 32 + (nn2 & 31)) * 8)) = o; }
;             else *(u32x4*)(WT + (size_t)dst_row<MAP>(n0 + n) * K + k0 + 8 * c) = o; } }
;     LDS_WAIT();
	s_and_b32 s6, s6, 0x1f00
	s_and_b32 s7, s11, 64
	ds_read2_b32 v[6:7], v71 offset0:65 offset1:73
	ds_read2_b32 v[8:9], v71 offset1:8
	ds_read2_b32 v[12:13], v71 offset0:130 offset1:138
	ds_read2_b32 v[14:15], v71 offset0:195 offset1:203
	ds_read2_b32 v[16:17], v96 offset0:4 offset1:12
	ds_read2_b32 v[18:19], v96 offset0:69 offset1:77
	ds_read2_b32 v[20:21], v96 offset0:134 offset1:142
	ds_read2_b32 v[22:23], v96 offset0:199 offset1:207
	s_or_b32 s6, s6, s7
	s_waitcnt lgkmcnt(0)
	v_cvt_pk_bf16_f32 v2, v8, v6
	v_or_b32_e32 v6, s6, v69
	v_lshlrev_b32_e32 v24, 11, v6
	v_mov_b32_e32 v25, v11
	v_lshl_add_u64 v[24:25], s[4:5], 0, v[24:25]
	s_lshl_b32 s64, s10, 1
	v_lshl_add_u64 v[24:25], v[24:25], 0, s[64:65]
	v_lshl_add_u64 v[24:25], v[24:25], 0, v[10:11]
	v_add_co_u32_e32 v24, vcc, s92, v24
	s_waitcnt lgkmcnt(4)
	v_cvt_pk_bf16_f32 v3, v12, v14
	s_waitcnt lgkmcnt(2)
	v_cvt_pk_bf16_f32 v4, v16, v18
	s_waitcnt lgkmcnt(0)
	v_cvt_pk_bf16_f32 v5, v20, v22
	v_addc_co_u32_e32 v25, vcc, 0, v25, vcc
	v_or_b32_e32 v6, s6, v72
	global_store_dwordx4 v[24:25], v[2:5], off
	v_lshlrev_b32_e32 v6, 11, v6
	s_nop 0
	v_cvt_pk_bf16_f32 v2, v9, v7
	v_mov_b32_e32 v7, v11
	v_lshl_add_u64 v[6:7], s[4:5], 0, v[6:7]
	v_lshl_add_u64 v[6:7], v[6:7], 0, s[64:65]
	v_lshl_add_u64 v[6:7], v[6:7], 0, v[10:11]
	v_add_co_u32_e32 v6, vcc, s92, v6
	v_cvt_pk_bf16_f32 v3, v13, v15
	v_cvt_pk_bf16_f32 v4, v17, v19
	v_cvt_pk_bf16_f32 v5, v21, v23
	v_addc_co_u32_e32 v7, vcc, 0, v7, vcc
	ds_read2_b32 v[8:9], v71 offset0:81 offset1:89
	ds_read2_b32 v[12:13], v71 offset0:16 offset1:24
	ds_read2_b32 v[14:15], v71 offset0:146 offset1:154
	ds_read2_b32 v[16:17], v71 offset0:211 offset1:219
	ds_read2_b32 v[18:19], v96 offset0:20 offset1:28
	ds_read2_b32 v[20:21], v96 offset0:85 offset1:93
	ds_read2_b32 v[22:23], v96 offset0:150 offset1:158
	ds_read2_b32 v[24:25], v96 offset0:215 offset1:223
	global_store_dwordx4 v[6:7], v[2:5], off
	v_or_b32_e32 v6, s6, v73
	v_lshlrev_b32_e32 v6, 11, v6
	v_mov_b32_e32 v7, v11
	v_lshl_add_u64 v[6:7], s[4:5], 0, v[6:7]
	v_lshl_add_u64 v[6:7], v[6:7], 0, s[64:65]
	v_lshl_add_u64 v[6:7], v[6:7], 0, v[10:11]
	v_add_co_u32_e32 v6, vcc, s92, v6
	s_waitcnt lgkmcnt(6)
	v_cvt_pk_bf16_f32 v2, v12, v8
	s_waitcnt lgkmcnt(4)
	v_cvt_pk_bf16_f32 v3, v14, v16
	s_waitcnt lgkmcnt(2)
	v_cvt_pk_bf16_f32 v4, v18, v20
	s_waitcnt lgkmcnt(0)
	v_cvt_pk_bf16_f32 v5, v22, v24
	v_addc_co_u32_e32 v7, vcc, 0, v7, vcc
	global_store_dwordx4 v[6:7], v[2:5], off
	v_or_b32_e32 v6, s6, v74
	v_lshlrev_b32_e32 v6, 11, v6
	v_mov_b32_e32 v7, v11
	v_lshl_add_u64 v[6:7], s[4:5], 0, v[6:7]
	v_lshl_add_u64 v[6:7], v[6:7], 0, s[64:65]
	v_lshl_add_u64 v[6:7], v[6:7], 0, v[10:11]
	v_add_co_u32_e32 v6, vcc, s92, v6
	v_cvt_pk_bf16_f32 v2, v13, v9
	v_cvt_pk_bf16_f32 v3, v15, v17
	v_cvt_pk_bf16_f32 v4, v19, v21
	v_cvt_pk_bf16_f32 v5, v23, v25
	v_addc_co_u32_e32 v7, vcc, 0, v7, vcc
	ds_read2_b32 v[8:9], v71 offset0:32 offset1:40
	ds_read2_b32 v[12:13], v71 offset0:97 offset1:105
	ds_read2_b32 v[14:15], v71 offset0:162 offset1:170
	ds_read2_b32 v[16:17], v71 offset0:227 offset1:235
	ds_read2_b32 v[18:19], v96 offset0:36 offset1:44
	ds_read2_b32 v[20:21], v96 offset0:101 offset1:109
	ds_read2_b32 v[22:23], v96 offset0:166 offset1:174
	ds_read2_b32 v[24:25], v96 offset0:231 offset1:239
	global_store_dwordx4 v[6:7], v[2:5], off
	v_or_b32_e32 v6, s6, v79
	v_lshlrev_b32_e32 v6, 11, v6
	v_mov_b32_e32 v7, v11
	v_lshl_add_u64 v[6:7], s[4:5], 0, v[6:7]
	v_lshl_add_u64 v[6:7], v[6:7], 0, s[64:65]
	v_lshl_add_u64 v[6:7], v[6:7], 0, v[10:11]
	v_add_co_u32_e32 v6, vcc, s92, v6
	s_waitcnt lgkmcnt(6)
	v_cvt_pk_bf16_f32 v2, v8, v12
	s_waitcnt lgkmcnt(4)
	v_cvt_pk_bf16_f32 v3, v14, v16
	s_waitcnt lgkmcnt(2)
	v_cvt_pk_bf16_f32 v4, v18, v20
	s_waitcnt lgkmcnt(0)
	v_cvt_pk_bf16_f32 v5, v22, v24
	v_addc_co_u32_e32 v7, vcc, 0, v7, vcc
	global_store_dwordx4 v[6:7], v[2:5], off
	v_or_b32_e32 v6, s6, v75
	v_lshlrev_b32_e32 v6, 11, v6
	v_mov_b32_e32 v7, v11
	v_lshl_add_u64 v[6:7], s[4:5], 0, v[6:7]
	v_lshl_add_u64 v[6:7], v[6:7], 0, s[64:65]
	v_lshl_add_u64 v[6:7], v[6:7], 0, v[10:11]
	v_add_co_u32_e32 v6, vcc, s92, v6
	v_cvt_pk_bf16_f32 v2, v9, v13
	v_cvt_pk_bf16_f32 v3, v15, v17
	v_cvt_pk_bf16_f32 v4, v19, v21
	v_cvt_pk_bf16_f32 v5, v23, v25
	v_addc_co_u32_e32 v7, vcc, 0, v7, vcc
	ds_read2_b32 v[8:9], v71 offset0:48 offset1:56
	ds_read2_b32 v[12:13], v71 offset0:113 offset1:121
	ds_read2_b32 v[14:15], v71 offset0:178 offset1:186
	ds_read2_b32 v[16:17], v71 offset0:243 offset1:251
	ds_read2_b32 v[18:19], v96 offset0:52 offset1:60
	ds_read2_b32 v[20:21], v96 offset0:117 offset1:125
	ds_read2_b32 v[22:23], v96 offset0:182 offset1:190
	ds_read2_b32 v[24:25], v96 offset0:247 offset1:255
	global_store_dwordx4 v[6:7], v[2:5], off
	v_or_b32_e32 v6, s6, v76
	v_lshlrev_b32_e32 v6, 11, v6
	v_mov_b32_e32 v7, v11
	v_lshl_add_u64 v[6:7], s[4:5], 0, v[6:7]
	v_lshl_add_u64 v[6:7], v[6:7], 0, s[64:65]
	v_lshl_add_u64 v[6:7], v[6:7], 0, v[10:11]
	v_add_co_u32_e32 v6, vcc, s92, v6
	s_waitcnt lgkmcnt(6)
	v_cvt_pk_bf16_f32 v2, v8, v12
	s_waitcnt lgkmcnt(4)
	v_cvt_pk_bf16_f32 v3, v14, v16
	s_waitcnt lgkmcnt(2)
	v_cvt_pk_bf16_f32 v4, v18, v20
	s_waitcnt lgkmcnt(0)
	v_cvt_pk_bf16_f32 v5, v22, v24
	v_addc_co_u32_e32 v7, vcc, 0, v7, vcc
	global_store_dwordx4 v[6:7], v[2:5], off
	v_or_b32_e32 v6, s6, v77
	v_lshlrev_b32_e32 v6, 11, v6
	v_mov_b32_e32 v7, v11
	v_lshl_add_u64 v[6:7], s[4:5], 0, v[6:7]
	v_lshl_add_u64 v[6:7], v[6:7], 0, s[64:65]
	v_lshl_add_u64 v[6:7], v[6:7], 0, v[10:11]
	v_add_co_u32_e32 v6, vcc, 0x40000, v6
	v_cvt_pk_bf16_f32 v2, v9, v13
	v_cvt_pk_bf16_f32 v3, v15, v17
	v_cvt_pk_bf16_f32 v4, v19, v21
	v_cvt_pk_bf16_f32 v5, v23, v25
	v_addc_co_u32_e32 v7, vcc, 0, v7, vcc
	global_store_dwordx4 v[6:7], v[2:5], off
	s_waitcnt lgkmcnt(0)

; #define LDS_WAIT() asm volatile("s_waitcnt lgkmcnt(0)" ::: "memory")
; template <int MAP> __device__ __forceinline__ void transpose_item(const float* W, int K, int N, const float* gk, bf16_t* WT, LAS float* scr, int item, int lane) {
;     ...
;     const int nn = n0 + lane; const bool okn = nn < N;
; #pragma unroll
;     for (int i = 0; i < 64; ++i) { float v = okn ? W[(size_t)(k0 + i) * N + nn] : 0.f; if (gk) v *= gk[k0 + i]; scr[i * 65 + lane] = v; }
;     LDS_WAIT();
.LBB0_156:
	s_andn2_b64 vcc, exec, s[4:5]
	s_cbranch_vccnz .LBB0_286
	s_mul_i32 s5, s78, 0xb00000
	s_mul_hi_i32 s4, s78, 0xb00000
	s_add_u32 s6, s56, s5
	s_addc_u32 s7, s57, s4
	s_lshl_b32 s4, s78, 10
	s_ashr_i32 s5, s4, 31
	s_lshl_b64 s[4:5], s[4:5], 2
	s_add_u32 s8, s54, s4
	s_addc_u32 s9, s55, s5
	s_add_i32 s4, s80, 0xfc10
	s_and_b32 s5, s4, 0xffff
	s_mul_i32 s5, s5, 0xba2f
	s_lshr_b32 s10, s5, 21
	s_mul_i32 s10, s10, 44
	s_sub_i32 s4, s4, s10
	s_lshr_b32 s5, s5, 15
	s_lshl_b32 s4, s4, 6
	s_and_b32 s10, s5, 0xffc0
	s_and_b32 s11, s4, 0xffc0
	v_or_b32_e32 v2, s11, v1
	s_mul_i32 s12, s10, 0xb00
	v_or_b32_e32 v3, s12, v2
	v_lshlrev_b32_e32 v3, 2, v3
	v_mov_b32_e32 v214, 1.0
	s_and_b64 vcc, exec, s[74:75]
	s_cbranch_vccz .Lpro_gate_nog
	v_lshlrev_b32_e32 v215, 2, v1
	v_lshl_add_u32 v215, s10, 2, v215
	global_load_dword v214, v215, s[8:9]
.Lpro_gate_nog:
	s_movk_i32 s32, 0x2c00
	global_load_dword v150, v3, s[6:7]
	v_add_u32_e32 v3, s32, v3
	global_load_dword v151, v3, s[6:7]
	v_add_u32_e32 v3, s32, v3
	global_load_dword v152, v3, s[6:7]
	v_add_u32_e32 v3, s32, v3
	global_load_dword v153, v3, s[6:7]
	v_add_u32_e32 v3, s32, v3
	global_load_dword v154, v3, s[6:7]
	v_add_u32_e32 v3, s32, v3
	global_load_dword v155, v3, s[6:7]
	v_add_u32_e32 v3, s32, v3
	global_load_dword v156, v3, s[6:7]
	v_add_u32_e32 v3, s32, v3
	global_load_dword v157, v3, s[6:7]
	v_add_u32_e32 v3, s32, v3
	global_load_dword v158, v3, s[6:7]
	v_add_u32_e32 v3, s32, v3
	global_load_dword v159, v3, s[6:7]
	v_add_u32_e32 v3, s32, v3
	global_load_dword v160, v3, s[6:7]
	v_add_u32_e32 v3, s32, v3
	global_load_dword v161, v3, s[6:7]
	v_add_u32_e32 v3, s32, v3
	global_load_dword v162, v3, s[6:7]
	v_add_u32_e32 v3, s32, v3
	global_load_dword v163, v3, s[6:7]
	v_add_u32_e32 v3, s32, v3
	global_load_dword v164, v3, s[6:7]
	v_add_u32_e32 v3, s32, v3
	global_load_dword v165, v3, s[6:7]
	v_add_u32_e32 v3, s32, v3
	global_load_dword v166, v3, s[6:7]
	v_add_u32_e32 v3, s32, v3
	global_load_dword v167, v3, s[6:7]
	v_add_u32_e32 v3, s32, v3
	global_load_dword v168, v3, s[6:7]
	v_add_u32_e32 v3, s32, v3
	global_load_dword v169, v3, s[6:7]
	v_add_u32_e32 v3, s32, v3
	global_load_dword v170, v3, s[6:7]
	v_add_u32_e32 v3, s32, v3
	global_load_dword v171, v3, s[6:7]
	v_add_u32_e32 v3, s32, v3
	global_load_dword v172, v3, s[6:7]
	v_add_u32_e32 v3, s32, v3
	global_load_dword v173, v3, s[6:7]
	v_add_u32_e32 v3, s32, v3
	global_load_dword v174, v3, s[6:7]
	v_add_u32_e32 v3, s32, v3
	global_load_dword v175, v3, s[6:7]
	v_add_u32_e32 v3, s32, v3
	global_load_dword v176, v3, s[6:7]
	v_add_u32_e32 v3, s32, v3
	global_load_dword v177, v3, s[6:7]
	v_add_u32_e32 v3, s32, v3
	global_load_dword v178, v3, s[6:7]
	v_add_u32_e32 v3, s32, v3
	global_load_dword v179, v3, s[6:7]
	v_add_u32_e32 v3, s32, v3
	global_load_dword v180, v3, s[6:7]
	v_add_u32_e32 v3, s32, v3
	global_load_dword v181, v3, s[6:7]
	v_add_u32_e32 v3, s32, v3
	global_load_dword v182, v3, s[6:7]
	v_add_u32_e32 v3, s32, v3
	global_load_dword v183, v3, s[6:7]
	v_add_u32_e32 v3, s32, v3
	global_load_dword v184, v3, s[6:7]
	v_add_u32_e32 v3, s32, v3
	global_load_dword v185, v3, s[6:7]
	v_add_u32_e32 v3, s32, v3
	global_load_dword v186, v3, s[6:7]
	v_add_u32_e32 v3, s32, v3
	global_load_dword v187, v3, s[6:7]
	v_add_u32_e32 v3, s32, v3
	global_load_dword v188, v3, s[6:7]
	v_add_u32_e32 v3, s32, v3
	global_load_dword v189, v3, s[6:7]
	v_add_u32_e32 v3, s32, v3
	global_load_dword v190, v3, s[6:7]
	v_add_u32_e32 v3, s32, v3
	global_load_dword v191, v3, s[6:7]
	v_add_u32_e32 v3, s32, v3
	global_load_dword v192, v3, s[6:7]
	v_add_u32_e32 v3, s32, v3
	global_load_dword v193, v3, s[6:7]
	v_add_u32_e32 v3, s32, v3
	global_load_dword v194, v3, s[6:7]
	v_add_u32_e32 v3, s32, v3
	global_load_dword v195, v3, s[6:7]
	v_add_u32_e32 v3, s32, v3
	global_load_dword v196, v3, s[6:7]
	v_add_u32_e32 v3, s32, v3
	global_load_dword v197, v3, s[6:7]
	v_add_u32_e32 v3, s32, v3
	global_load_dword v198, v3, s[6:7]
	v_add_u32_e32 v3, s32, v3
	global_load_dword v199, v3, s[6:7]
	v_add_u32_e32 v3, s32, v3
	global_load_dword v200, v3, s[6:7]
	v_add_u32_e32 v3, s32, v3
	global_load_dword v201, v3, s[6:7]
	v_add_u32_e32 v3, s32, v3
	global_load_dword v202, v3, s[6:7]
	v_add_u32_e32 v3, s32, v3
	global_load_dword v203, v3, s[6:7]
	v_add_u32_e32 v3, s32, v3
	global_load_dword v204, v3, s[6:7]
	v_add_u32_e32 v3, s32, v3
	global_load_dword v205, v3, s[6:7]
	v_add_u32_e32 v3, s32, v3
	global_load_dword v206, v3, s[6:7]
	v_add_u32_e32 v3, s32, v3
	global_load_dword v207, v3, s[6:7]
	v_add_u32_e32 v3, s32, v3
	global_load_dword v208, v3, s[6:7]
	v_add_u32_e32 v3, s32, v3
	global_load_dword v209, v3, s[6:7]
	v_add_u32_e32 v3, s32, v3
	global_load_dword v210, v3, s[6:7]
	v_add_u32_e32 v3, s32, v3
	global_load_dword v211, v3, s[6:7]
	v_add_u32_e32 v3, s32, v3
	global_load_dword v212, v3, s[6:7]
	v_add_u32_e32 v3, s32, v3
	global_load_dword v213, v3, s[6:7]
	v_add_u32_e32 v3, s32, v3
	s_waitcnt vmcnt(60)
	v_readlane_b32 s98, v214, 0
	v_readlane_b32 s99, v214, 1
	v_readlane_b32 s100, v214, 2
	v_readlane_b32 s101, v214, 3
	v_mul_f32_e32 v150, s98, v150
	v_mul_f32_e32 v151, s99, v151
	v_mul_f32_e32 v152, s100, v152
	v_mul_f32_e32 v153, s101, v153
	ds_write_b32 v68, v150
	ds_write_b32 v68, v151 offset:260
	ds_write_b32 v68, v152 offset:520
	ds_write_b32 v68, v153 offset:780
	s_waitcnt vmcnt(56)
	v_readlane_b32 s98, v214, 4
	v_readlane_b32 s99, v214, 5
	v_readlane_b32 s100, v214, 6
	v_readlane_b32 s101, v214, 7
	v_mul_f32_e32 v154, s98, v154
	v_mul_f32_e32 v155, s99, v155
	v_mul_f32_e32 v156, s100, v156
	v_mul_f32_e32 v157, s101, v157
	ds_write_b32 v68, v154 offset:1040
	ds_write_b32 v68, v155 offset:1300
	ds_write_b32 v68, v156 offset:1560
	ds_write_b32 v68, v157 offset:1820
	s_waitcnt vmcnt(52)
; #define LDS_WAIT() asm volatile("s_waitcnt lgkmcnt(0)" ::: "memory")
; template <int MAP> __device__ __forceinline__ void transpose_item(const float* W, int K, int N, const float* gk, bf16_t* WT, LAS float* scr, int item, int lane) {
;     ...
;     const int nn = n0 + lane; const bool okn = nn < N;
; #pragma unroll
;     for (int i = 0; i < 64; ++i) { float v = okn ? W[(size_t)(k0 + i) * N + nn] : 0.f; if (gk) v *= gk[k0 + i]; scr[i * 65 + lane] = v; }
;     LDS_WAIT();
	v_readlane_b32 s98, v214, 8
	v_readlane_b32 s99, v214, 9
	v_readlane_b32 s100, v214, 10
	v_readlane_b32 s101, v214, 11
	v_mul_f32_e32 v158, s98, v158
	v_mul_f32_e32 v159, s99, v159
	v_mul_f32_e32 v160, s100, v160
	v_mul_f32_e32 v161, s101, v161
	ds_write_b32 v68, v158 offset:2080
	ds_write_b32 v68, v159 offset:2340
	ds_write_b32 v68, v160 offset:2600
	ds_write_b32 v68, v161 offset:2860
	s_waitcnt vmcnt(48)
	v_readlane_b32 s98, v214, 12
	v_readlane_b32 s99, v214, 13
	v_readlane_b32 s100, v214, 14
	v_readlane_b32 s101, v214, 15
	v_mul_f32_e32 v162, s98, v162
	v_mul_f32_e32 v163, s99, v163
	v_mul_f32_e32 v164, s100, v164
	v_mul_f32_e32 v165, s101, v165
	ds_write_b32 v68, v162 offset:3120
	ds_write_b32 v68, v163 offset:3380
	ds_write_b32 v68, v164 offset:3640
	ds_write_b32 v68, v165 offset:3900
	s_waitcnt vmcnt(44)
	v_readlane_b32 s98, v214, 16
	v_readlane_b32 s99, v214, 17
	v_readlane_b32 s100, v214, 18
	v_readlane_b32 s101, v214, 19
	v_mul_f32_e32 v166, s98, v166
	v_mul_f32_e32 v167, s99, v167
	v_mul_f32_e32 v168, s100, v168
	v_mul_f32_e32 v169, s101, v169
	ds_write_b32 v68, v166 offset:4160
	ds_write_b32 v68, v167 offset:4420
	ds_write_b32 v68, v168 offset:4680
	ds_write_b32 v68, v169 offset:4940
	s_waitcnt vmcnt(40)
	v_readlane_b32 s98, v214, 20
	v_readlane_b32 s99, v214, 21
	v_readlane_b32 s100, v214, 22
	v_readlane_b32 s101, v214, 23
	v_mul_f32_e32 v170, s98, v170
	v_mul_f32_e32 v171, s99, v171
	v_mul_f32_e32 v172, s100, v172
	v_mul_f32_e32 v173, s101, v173
	ds_write_b32 v68, v170 offset:5200
	ds_write_b32 v68, v171 offset:5460
	ds_write_b32 v68, v172 offset:5720
	ds_write_b32 v68, v173 offset:5980
	s_waitcnt vmcnt(36)
	v_readlane_b32 s98, v214, 24
	v_readlane_b32 s99, v214, 25
	v_readlane_b32 s100, v214, 26
	v_readlane_b32 s101, v214, 27
	v_mul_f32_e32 v174, s98, v174
	v_mul_f32_e32 v175, s99, v175
	v_mul_f32_e32 v176, s100, v176
	v_mul_f32_e32 v177, s101, v177
	ds_write_b32 v68, v174 offset:6240
	ds_write_b32 v68, v175 offset:6500
	ds_write_b32 v68, v176 offset:6760
	ds_write_b32 v68, v177 offset:7020
	s_waitcnt vmcnt(32)
	v_readlane_b32 s98, v214, 28
	v_readlane_b32 s99, v214, 29
	v_readlane_b32 s100, v214, 30
	v_readlane_b32 s101, v214, 31
	v_mul_f32_e32 v178, s98, v178
	v_mul_f32_e32 v179, s99, v179
	v_mul_f32_e32 v180, s100, v180
	v_mul_f32_e32 v181, s101, v181
	ds_write_b32 v68, v178 offset:7280
	ds_write_b32 v68, v179 offset:7540
	ds_write_b32 v68, v180 offset:7800
	ds_write_b32 v68, v181 offset:8060
	s_waitcnt vmcnt(28)
	v_readlane_b32 s98, v214, 32
	v_readlane_b32 s99, v214, 33
	v_readlane_b32 s100, v214, 34
	v_readlane_b32 s101, v214, 35
	v_mul_f32_e32 v182, s98, v182
	v_mul_f32_e32 v183, s99, v183
	v_mul_f32_e32 v184, s100, v184
	v_mul_f32_e32 v185, s101, v185
	ds_write_b32 v68, v182 offset:8320
	ds_write_b32 v68, v183 offset:8580
	ds_write_b32 v68, v184 offset:8840
	ds_write_b32 v68, v185 offset:9100
	s_waitcnt vmcnt(24)
	v_readlane_b32 s98, v214, 36
	v_readlane_b32 s99, v214, 37
	v_readlane_b32 s100, v214, 38
	v_readlane_b32 s101, v214, 39
	v_mul_f32_e32 v186, s98, v186
	v_mul_f32_e32 v187, s99, v187
	v_mul_f32_e32 v188, s100, v188
	v_mul_f32_e32 v189, s101, v189
	ds_write_b32 v68, v186 offset:9360
	ds_write_b32 v68, v187 offset:9620
	ds_write_b32 v68, v188 offset:9880
	ds_write_b32 v68, v189 offset:10140
	s_waitcnt vmcnt(20)
	v_readlane_b32 s98, v214, 40
	v_readlane_b32 s99, v214, 41
	v_readlane_b32 s100, v214, 42
	v_readlane_b32 s101, v214, 43
	v_mul_f32_e32 v190, s98, v190
	v_mul_f32_e32 v191, s99, v191
	v_mul_f32_e32 v192, s100, v192
	v_mul_f32_e32 v193, s101, v193
	ds_write_b32 v68, v190 offset:10400
	ds_write_b32 v68, v191 offset:10660
	ds_write_b32 v68, v192 offset:10920
	ds_write_b32 v68, v193 offset:11180
	s_waitcnt vmcnt(16)
	v_readlane_b32 s98, v214, 44
	v_readlane_b32 s99, v214, 45
	v_readlane_b32 s100, v214, 46
	v_readlane_b32 s101, v214, 47
	v_mul_f32_e32 v194, s98, v194
	v_mul_f32_e32 v195, s99, v195
	v_mul_f32_e32 v196, s100, v196
	v_mul_f32_e32 v197, s101, v197
	ds_write_b32 v68, v194 offset:11440
	ds_write_b32 v68, v195 offset:11700
	ds_write_b32 v68, v196 offset:11960
	ds_write_b32 v68, v197 offset:12220
	s_waitcnt vmcnt(12)
	v_readlane_b32 s98, v214, 48
	v_readlane_b32 s99, v214, 49
	v_readlane_b32 s100, v214, 50
	v_readlane_b32 s101, v214, 51
	v_mul_f32_e32 v198, s98, v198
	v_mul_f32_e32 v199, s99, v199
	v_mul_f32_e32 v200, s100, v200
	v_mul_f32_e32 v201, s101, v201
	ds_write_b32 v68, v198 offset:12480
	ds_write_b32 v68, v199 offset:12740
	ds_write_b32 v68, v200 offset:13000
	ds_write_b32 v68, v201 offset:13260
	s_waitcnt vmcnt(8)
	v_readlane_b32 s98, v214, 52
	v_readlane_b32 s99, v214, 53
	v_readlane_b32 s100, v214, 54
	v_readlane_b32 s101, v214, 55
	v_mul_f32_e32 v202, s98, v202
	v_mul_f32_e32 v203, s99, v203
	v_mul_f32_e32 v204, s100, v204
	v_mul_f32_e32 v205, s101, v205
	ds_write_b32 v68, v202 offset:13520
	ds_write_b32 v68, v203 offset:13780
	ds_write_b32 v68, v204 offset:14040
	ds_write_b32 v68, v205 offset:14300
	s_waitcnt vmcnt(4)
	v_readlane_b32 s98, v214, 56
	v_readlane_b32 s99, v214, 57
	v_readlane_b32 s100, v214, 58
	v_readlane_b32 s101, v214, 59
	v_mul_f32_e32 v206, s98, v206
	v_mul_f32_e32 v207, s99, v207
	v_mul_f32_e32 v208, s100, v208
	v_mul_f32_e32 v209, s101, v209
	ds_write_b32 v68, v206 offset:14560
	ds_write_b32 v68, v207 offset:14820
	ds_write_b32 v68, v208 offset:15080
	ds_write_b32 v68, v209 offset:15340
	s_waitcnt vmcnt(0)
; #define LAS __attribute__((address_space(3)))
; __device__ __forceinline__ unsigned pk2(float lo, float hi) { pk_f32x2_t v = {lo, hi}; pk_bf16x2_t b = __builtin_convertvector(v, pk_bf16x2_t); return __builtin_bit_cast(unsigned, b); }
; #define LDS_WAIT() asm volatile("s_waitcnt lgkmcnt(0)" ::: "memory")
; template <int MAP> __device__ __forceinline__ void transpose_item(const float* W, int K, int N, const float* gk, bf16_t* WT, LAS float* scr, int item, int lane) {
;     ...
;     const int c = lane & 7;
; #pragma unroll
;     for (int j = 0; j < 8; ++j) { const int n = (lane >> 3) + 8 * j; const LAS float* s = scr + (8 * c) * 65 + n;
;         if (n0 + n < N) { u32x4 o; o.x = pk2(s[0 * 65], s[1 * 65]); o.y = pk2(s[2 * 65], s[3 * 65]); o.z = pk2(s[4 * 65], s[5 * 65]); o.w = pk2(s[6 * 65], s[7 * 65]);
;             if (MAP == 4) { const int nn2 = n0 + n, kk2 = k0 + 8 * c; *(u32x4*)(WT + ((size_t)(((nn2 >> 5) * (K >> 4) + (kk2 >> 4)) * 64 + ((kk2 >> 3) & 1) * 32 + (nn2 & 31)) * 8)) = o; }
;             else *(u32x4*)(WT + (size_t)dst_row<MAP>(n0 + n) * K + k0 + 8 * c) = o; } }
;     LDS_WAIT();
	v_readlane_b32 s98, v214, 60
	v_readlane_b32 s99, v214, 61
	v_readlane_b32 s100, v214, 62
	v_readlane_b32 s101, v214, 63
	v_mul_f32_e32 v210, s98, v210
	v_mul_f32_e32 v211, s99, v211
	v_mul_f32_e32 v212, s100, v212
	v_mul_f32_e32 v213, s101, v213
	ds_write_b32 v68, v210 offset:15600
	ds_write_b32 v68, v211 offset:15860
	ds_write_b32 v68, v212 offset:16120
	ds_write_b32 v68, v213 offset:16380
	s_lshl_b32 s4, s11, 1
	s_and_b32 s4, s4, 0x1f00
	s_and_b32 s5, s11, 64
	s_waitcnt lgkmcnt(0)
	s_or_b32 s6, s4, s5
	s_lshl_b32 s4, s10, 1
	s_add_u32 s4, s97, s4
	ds_read2_b32 v[6:7], v71 offset0:65 offset1:73
	ds_read2_b32 v[8:9], v71 offset1:8
	ds_read2_b32 v[12:13], v71 offset0:130 offset1:138
	ds_read2_b32 v[14:15], v71 offset0:195 offset1:203
	ds_read2_b32 v[16:17], v96 offset0:4 offset1:12
	ds_read2_b32 v[18:19], v96 offset0:69 offset1:77
	ds_read2_b32 v[20:21], v96 offset0:134 offset1:142
	ds_read2_b32 v[22:23], v96 offset0:199 offset1:207
	s_addc_u32 s5, s71, 0
	v_lshl_add_u64 v[2:3], s[4:5], 0, v[10:11]
	s_mov_b64 s[4:5], 0x800000
	v_lshl_add_u64 v[24:25], v[2:3], 0, s[4:5]
	s_waitcnt lgkmcnt(0)
	v_cvt_pk_bf16_f32 v2, v8, v6
	v_or_b32_e32 v6, s6, v69
	v_lshlrev_b32_e32 v26, 11, v6
	v_mov_b32_e32 v27, v11
	s_waitcnt lgkmcnt(4)
	v_cvt_pk_bf16_f32 v3, v12, v14
	s_waitcnt lgkmcnt(2)
	v_cvt_pk_bf16_f32 v4, v16, v18
	s_waitcnt lgkmcnt(0)
	v_cvt_pk_bf16_f32 v5, v20, v22
	v_lshl_add_u64 v[26:27], v[24:25], 0, v[26:27]
	global_store_dwordx4 v[26:27], v[2:5], off
	v_or_b32_e32 v6, s6, v72
	v_lshlrev_b32_e32 v6, 11, v6
	v_cvt_pk_bf16_f32 v2, v9, v7
	v_cvt_pk_bf16_f32 v3, v13, v15
	v_cvt_pk_bf16_f32 v4, v17, v19
	v_cvt_pk_bf16_f32 v5, v21, v23
	ds_read2_b32 v[8:9], v71 offset0:81 offset1:89
	ds_read2_b32 v[12:13], v71 offset0:16 offset1:24
	ds_read2_b32 v[14:15], v71 offset0:146 offset1:154
	ds_read2_b32 v[16:17], v71 offset0:211 offset1:219
	ds_read2_b32 v[18:19], v96 offset0:20 offset1:28
	ds_read2_b32 v[20:21], v96 offset0:85 offset1:93
	ds_read2_b32 v[22:23], v96 offset0:150 offset1:158
	ds_read2_b32 v[26:27], v96 offset0:215 offset1:223
	v_mov_b32_e32 v7, v11
	v_lshl_add_u64 v[6:7], v[24:25], 0, v[6:7]
	global_store_dwordx4 v[6:7], v[2:5], off
	v_or_b32_e32 v6, s6, v73
	v_lshlrev_b32_e32 v6, 11, v6
	v_mov_b32_e32 v7, v11
	s_waitcnt lgkmcnt(6)
	v_cvt_pk_bf16_f32 v2, v12, v8
	s_waitcnt lgkmcnt(4)
	v_cvt_pk_bf16_f32 v3, v14, v16
	s_waitcnt lgkmcnt(2)
	v_cvt_pk_bf16_f32 v4, v18, v20
	s_waitcnt lgkmcnt(0)
	v_cvt_pk_bf16_f32 v5, v22, v26
	v_lshl_add_u64 v[6:7], v[24:25], 0, v[6:7]
	global_store_dwordx4 v[6:7], v[2:5], off
	v_or_b32_e32 v6, s6, v74
	v_lshlrev_b32_e32 v6, 11, v6
	v_cvt_pk_bf16_f32 v2, v13, v9
	v_cvt_pk_bf16_f32 v3, v15, v17
	v_cvt_pk_bf16_f32 v4, v19, v21
	v_cvt_pk_bf16_f32 v5, v23, v27
	ds_read2_b32 v[8:9], v71 offset0:32 offset1:40
	ds_read2_b32 v[12:13], v71 offset0:97 offset1:105
	ds_read2_b32 v[14:15], v71 offset0:162 offset1:170
	ds_read2_b32 v[16:17], v71 offset0:227 offset1:235
	ds_read2_b32 v[18:19], v96 offset0:36 offset1:44
	ds_read2_b32 v[20:21], v96 offset0:101 offset1:109
	ds_read2_b32 v[22:23], v96 offset0:166 offset1:174
	ds_read2_b32 v[26:27], v96 offset0:231 offset1:239
	v_mov_b32_e32 v7, v11
	v_lshl_add_u64 v[6:7], v[24:25], 0, v[6:7]
	global_store_dwordx4 v[6:7], v[2:5], off
	v_or_b32_e32 v6, s6, v79
	v_lshlrev_b32_e32 v6, 11, v6
	v_mov_b32_e32 v7, v11
	s_waitcnt lgkmcnt(6)
	v_cvt_pk_bf16_f32 v2, v8, v12
	s_waitcnt lgkmcnt(4)
	v_cvt_pk_bf16_f32 v3, v14, v16
	s_waitcnt lgkmcnt(2)
	v_cvt_pk_bf16_f32 v4, v18, v20
	s_waitcnt lgkmcnt(0)
	v_cvt_pk_bf16_f32 v5, v22, v26
	v_lshl_add_u64 v[6:7], v[24:25], 0, v[6:7]
	global_store_dwordx4 v[6:7], v[2:5], off
	v_or_b32_e32 v6, s6, v75
	v_lshlrev_b32_e32 v6, 11, v6
	v_cvt_pk_bf16_f32 v2, v9, v13
	v_cvt_pk_bf16_f32 v3, v15, v17
	v_cvt_pk_bf16_f32 v4, v19, v21
	v_cvt_pk_bf16_f32 v5, v23, v27
	ds_read2_b32 v[8:9], v71 offset0:48 offset1:56
	ds_read2_b32 v[12:13], v71 offset0:113 offset1:121
	ds_read2_b32 v[14:15], v71 offset0:178 offset1:186
	ds_read2_b32 v[16:17], v71 offset0:243 offset1:251
	ds_read2_b32 v[18:19], v96 offset0:52 offset1:60
	ds_read2_b32 v[20:21], v96 offset0:117 offset1:125
	ds_read2_b32 v[22:23], v96 offset0:182 offset1:190
	ds_read2_b32 v[26:27], v96 offset0:247 offset1:255
	v_mov_b32_e32 v7, v11
	v_lshl_add_u64 v[6:7], v[24:25], 0, v[6:7]
	global_store_dwordx4 v[6:7], v[2:5], off
	v_or_b32_e32 v6, s6, v76
	v_lshlrev_b32_e32 v6, 11, v6
	v_mov_b32_e32 v7, v11
	s_waitcnt lgkmcnt(6)
	v_cvt_pk_bf16_f32 v2, v8, v12
	s_waitcnt lgkmcnt(4)
	v_cvt_pk_bf16_f32 v3, v14, v16
	s_waitcnt lgkmcnt(2)
	v_cvt_pk_bf16_f32 v4, v18, v20
	s_waitcnt lgkmcnt(0)
	v_cvt_pk_bf16_f32 v5, v22, v26
	v_lshl_add_u64 v[6:7], v[24:25], 0, v[6:7]
	global_store_dwordx4 v[6:7], v[2:5], off
	v_or_b32_e32 v6, s6, v77
	v_lshlrev_b32_e32 v6, 11, v6
	v_mov_b32_e32 v7, v11
	v_cvt_pk_bf16_f32 v2, v9, v13
	v_cvt_pk_bf16_f32 v3, v15, v17
	v_cvt_pk_bf16_f32 v4, v19, v21
	v_cvt_pk_bf16_f32 v5, v23, v27
	v_lshl_add_u64 v[6:7], v[24:25], 0, v[6:7]
	global_store_dwordx4 v[6:7], v[2:5], off
	s_waitcnt lgkmcnt(0)

; #define LDS_WAIT() asm volatile("s_waitcnt lgkmcnt(0)" ::: "memory")
; template <int MAP> __device__ __forceinline__ void transpose_item(const float* W, int K, int N, const float* gk, bf16_t* WT, LAS float* scr, int item, int lane) {
;     const int nblk = (N + 63) / 64, kb = item / nblk, nb = item % nblk, k0 = 64 * kb, n0 = 64 * nb;
;     const int nn = n0 + lane; const bool okn = nn < N;
; #pragma unroll
;     for (int i = 0; i < 64; ++i) { float v = okn ? W[(size_t)(k0 + i) * N + nn] : 0.f; if (gk) v *= gk[k0 + i]; scr[i * 65 + lane] = v; }
;     LDS_WAIT();
.LBB0_291:
	s_mul_i32 s4, s78, 0xb8c000
	s_mul_hi_i32 s5, s78, 0xb8c000
	s_add_u32 s4, s72, s4
	s_mul_i32 s6, s80, 0xffffae4d
	s_addc_u32 s5, s73, s5
	s_lshr_b32 s6, s6, 16
	s_add_i32 s6, s6, s80
	s_sext_i32_i16 s7, s6
	s_ashr_i32 s7, s7, 5
	s_bfe_u32 s6, s6, 0x1000f
	s_add_i32 s6, s7, s6
	s_sext_i32_i16 s8, s6
	s_mul_i32 s6, s6, 47
	s_sub_i32 s6, s80, s6
	s_sext_i32_i16 s6, s6
	s_lshl_b32 s14, s6, 6
	v_or_b32_e32 v2, s14, v1
	v_ashrrev_i32_e32 v3, 31, v2
	v_cmp_gt_i32_e64 s[6:7], s93, v2
	v_lshl_add_u64 v[2:3], v[2:3], 2, s[4:5]
	s_mul_i32 s10, s8, 0xb8c00
	s_ashr_i32 s11, s10, 31
	s_lshl_b32 s4, s78, 10
	s_ashr_i32 s5, s4, 31
	s_lshl_b64 s[4:5], s[4:5], 2
	s_add_u32 s12, s62, s4
	s_addc_u32 s13, s63, s5
	s_lshl_b32 s8, s8, 6
	s_ashr_i32 s9, s8, 31
	v_mov_b32_e32 v214, 1.0
	s_and_b64 vcc, exec, s[76:77]
	s_cbranch_vccz .Lpro_in_nog
	v_lshlrev_b32_e32 v215, 2, v1
	v_lshl_add_u32 v215, s8, 2, v215
	global_load_dword v214, v215, s[12:13]
.Lpro_in_nog:
	v_lshl_add_u64 v[216:217], v[2:3], 0, s[10:11]
	s_movk_i32 s100, 0x2e30
	s_mov_b32 s101, 0
	v_mov_b32_e32 v150, 0
	v_mov_b32_e32 v151, 0
	v_mov_b32_e32 v152, 0
	v_mov_b32_e32 v153, 0
	v_mov_b32_e32 v154, 0
	v_mov_b32_e32 v155, 0
	v_mov_b32_e32 v156, 0
	v_mov_b32_e32 v157, 0
	v_mov_b32_e32 v158, 0
	v_mov_b32_e32 v159, 0
	v_mov_b32_e32 v160, 0
	v_mov_b32_e32 v161, 0
	v_mov_b32_e32 v162, 0
	v_mov_b32_e32 v163, 0
	v_mov_b32_e32 v164, 0
	v_mov_b32_e32 v165, 0
	v_mov_b32_e32 v166, 0
	v_mov_b32_e32 v167, 0
	v_mov_b32_e32 v168, 0
	v_mov_b32_e32 v169, 0
	v_mov_b32_e32 v170, 0
	v_mov_b32_e32 v171, 0
	v_mov_b32_e32 v172, 0
	v_mov_b32_e32 v173, 0
	v_mov_b32_e32 v174, 0
	v_mov_b32_e32 v175, 0
	v_mov_b32_e32 v176, 0
	v_mov_b32_e32 v177, 0
	v_mov_b32_e32 v178, 0
	v_mov_b32_e32 v179, 0
	v_mov_b32_e32 v180, 0
	v_mov_b32_e32 v181, 0
	v_mov_b32_e32 v182, 0
	v_mov_b32_e32 v183, 0
	v_mov_b32_e32 v184, 0
	v_mov_b32_e32 v185, 0
	v_mov_b32_e32 v186, 0
	v_mov_b32_e32 v187, 0
	v_mov_b32_e32 v188, 0
	v_mov_b32_e32 v189, 0
	v_mov_b32_e32 v190, 0
	v_mov_b32_e32 v191, 0
	v_mov_b32_e32 v192, 0
	v_mov_b32_e32 v193, 0
	v_mov_b32_e32 v194, 0
	v_mov_b32_e32 v195, 0
	v_mov_b32_e32 v196, 0
	v_mov_b32_e32 v197, 0
	v_mov_b32_e32 v198, 0
	v_mov_b32_e32 v199, 0
	v_mov_b32_e32 v200, 0
	v_mov_b32_e32 v201, 0
	v_mov_b32_e32 v202, 0
	v_mov_b32_e32 v203, 0
	v_mov_b32_e32 v204, 0
	v_mov_b32_e32 v205, 0
	v_mov_b32_e32 v206, 0
	v_mov_b32_e32 v207, 0
	v_mov_b32_e32 v208, 0
	v_mov_b32_e32 v209, 0
	v_mov_b32_e32 v210, 0
	v_mov_b32_e32 v211, 0
	v_mov_b32_e32 v212, 0
	v_mov_b32_e32 v213, 0
	s_and_saveexec_b64 s[98:99], s[6:7]
	global_load_dword v150, v[216:217], off
	v_lshl_add_u64 v[216:217], v[216:217], 0, s[100:101]
	global_load_dword v151, v[216:217], off
	v_lshl_add_u64 v[216:217], v[216:217], 0, s[100:101]
	global_load_dword v152, v[216:217], off
	v_lshl_add_u64 v[216:217], v[216:217], 0, s[100:101]
	global_load_dword v153, v[216:217], off
	v_lshl_add_u64 v[216:217], v[216:217], 0, s[100:101]
	global_load_dword v154, v[216:217], off
	v_lshl_add_u64 v[216:217], v[216:217], 0, s[100:101]
	global_load_dword v155, v[216:217], off
	v_lshl_add_u64 v[216:217], v[216:217], 0, s[100:101]
	global_load_dword v156, v[216:217], off
	v_lshl_add_u64 v[216:217], v[216:217], 0, s[100:101]
	global_load_dword v157, v[216:217], off
	v_lshl_add_u64 v[216:217], v[216:217], 0, s[100:101]
	global_load_dword v158, v[216:217], off
	v_lshl_add_u64 v[216:217], v[216:217], 0, s[100:101]
	global_load_dword v159, v[216:217], off
	v_lshl_add_u64 v[216:217], v[216:217], 0, s[100:101]
	global_load_dword v160, v[216:217], off
	v_lshl_add_u64 v[216:217], v[216:217], 0, s[100:101]
	global_load_dword v161, v[216:217], off
	v_lshl_add_u64 v[216:217], v[216:217], 0, s[100:101]
	global_load_dword v162, v[216:217], off
	v_lshl_add_u64 v[216:217], v[216:217], 0, s[100:101]
	global_load_dword v163, v[216:217], off
	v_lshl_add_u64 v[216:217], v[216:217], 0, s[100:101]
	global_load_dword v164, v[216:217], off
	v_lshl_add_u64 v[216:217], v[216:217], 0, s[100:101]
	global_load_dword v165, v[216:217], off
	v_lshl_add_u64 v[216:217], v[216:217], 0, s[100:101]
	global_load_dword v166, v[216:217], off
	v_lshl_add_u64 v[216:217], v[216:217], 0, s[100:101]
	global_load_dword v167, v[216:217], off
	v_lshl_add_u64 v[216:217], v[216:217], 0, s[100:101]
	global_load_dword v168, v[216:217], off
	v_lshl_add_u64 v[216:217], v[216:217], 0, s[100:101]
	global_load_dword v169, v[216:217], off
	v_lshl_add_u64 v[216:217], v[216:217], 0, s[100:101]
	global_load_dword v170, v[216:217], off
	v_lshl_add_u64 v[216:217], v[216:217], 0, s[100:101]
	global_load_dword v171, v[216:217], off
	v_lshl_add_u64 v[216:217], v[216:217], 0, s[100:101]
	global_load_dword v172, v[216:217], off
	v_lshl_add_u64 v[216:217], v[216:217], 0, s[100:101]
	global_load_dword v173, v[216:217], off
	v_lshl_add_u64 v[216:217], v[216:217], 0, s[100:101]
	global_load_dword v174, v[216:217], off
	v_lshl_add_u64 v[216:217], v[216:217], 0, s[100:101]
	global_load_dword v175, v[216:217], off
	v_lshl_add_u64 v[216:217], v[216:217], 0, s[100:101]
	global_load_dword v176, v[216:217], off
	v_lshl_add_u64 v[216:217], v[216:217], 0, s[100:101]
	global_load_dword v177, v[216:217], off
	v_lshl_add_u64 v[216:217], v[216:217], 0, s[100:101]
	global_load_dword v178, v[216:217], off
	v_lshl_add_u64 v[216:217], v[216:217], 0, s[100:101]
	global_load_dword v179, v[216:217], off
	v_lshl_add_u64 v[216:217], v[216:217], 0, s[100:101]
	global_load_dword v180, v[216:217], off
	v_lshl_add_u64 v[216:217], v[216:217], 0, s[100:101]
	global_load_dword v181, v[216:217], off
	v_lshl_add_u64 v[216:217], v[216:217], 0, s[100:101]
	global_load_dword v182, v[216:217], off
; #define LDS_WAIT() asm volatile("s_waitcnt lgkmcnt(0)" ::: "memory")
; template <int MAP> __device__ __forceinline__ void transpose_item(const float* W, int K, int N, const float* gk, bf16_t* WT, LAS float* scr, int item, int lane) {
;     const int nblk = (N + 63) / 64, kb = item / nblk, nb = item % nblk, k0 = 64 * kb, n0 = 64 * nb;
;     const int nn = n0 + lane; const bool okn = nn < N;
; #pragma unroll
;     for (int i = 0; i < 64; ++i) { float v = okn ? W[(size_t)(k0 + i) * N + nn] : 0.f; if (gk) v *= gk[k0 + i]; scr[i * 65 + lane] = v; }
;     LDS_WAIT();
	v_lshl_add_u64 v[216:217], v[216:217], 0, s[100:101]
	global_load_dword v183, v[216:217], off
	v_lshl_add_u64 v[216:217], v[216:217], 0, s[100:101]
	global_load_dword v184, v[216:217], off
	v_lshl_add_u64 v[216:217], v[216:217], 0, s[100:101]
	global_load_dword v185, v[216:217], off
	v_lshl_add_u64 v[216:217], v[216:217], 0, s[100:101]
	global_load_dword v186, v[216:217], off
	v_lshl_add_u64 v[216:217], v[216:217], 0, s[100:101]
	global_load_dword v187, v[216:217], off
	v_lshl_add_u64 v[216:217], v[216:217], 0, s[100:101]
	global_load_dword v188, v[216:217], off
	v_lshl_add_u64 v[216:217], v[216:217], 0, s[100:101]
	global_load_dword v189, v[216:217], off
	v_lshl_add_u64 v[216:217], v[216:217], 0, s[100:101]
	global_load_dword v190, v[216:217], off
	v_lshl_add_u64 v[216:217], v[216:217], 0, s[100:101]
	global_load_dword v191, v[216:217], off
	v_lshl_add_u64 v[216:217], v[216:217], 0, s[100:101]
	global_load_dword v192, v[216:217], off
	v_lshl_add_u64 v[216:217], v[216:217], 0, s[100:101]
	global_load_dword v193, v[216:217], off
	v_lshl_add_u64 v[216:217], v[216:217], 0, s[100:101]
	global_load_dword v194, v[216:217], off
	v_lshl_add_u64 v[216:217], v[216:217], 0, s[100:101]
	global_load_dword v195, v[216:217], off
	v_lshl_add_u64 v[216:217], v[216:217], 0, s[100:101]
	global_load_dword v196, v[216:217], off
	v_lshl_add_u64 v[216:217], v[216:217], 0, s[100:101]
	global_load_dword v197, v[216:217], off
	v_lshl_add_u64 v[216:217], v[216:217], 0, s[100:101]
	global_load_dword v198, v[216:217], off
	v_lshl_add_u64 v[216:217], v[216:217], 0, s[100:101]
	global_load_dword v199, v[216:217], off
	v_lshl_add_u64 v[216:217], v[216:217], 0, s[100:101]
	global_load_dword v200, v[216:217], off
	v_lshl_add_u64 v[216:217], v[216:217], 0, s[100:101]
	global_load_dword v201, v[216:217], off
	v_lshl_add_u64 v[216:217], v[216:217], 0, s[100:101]
	global_load_dword v202, v[216:217], off
	v_lshl_add_u64 v[216:217], v[216:217], 0, s[100:101]
	global_load_dword v203, v[216:217], off
	v_lshl_add_u64 v[216:217], v[216:217], 0, s[100:101]
	global_load_dword v204, v[216:217], off
	v_lshl_add_u64 v[216:217], v[216:217], 0, s[100:101]
	global_load_dword v205, v[216:217], off
	v_lshl_add_u64 v[216:217], v[216:217], 0, s[100:101]
	global_load_dword v206, v[216:217], off
	v_lshl_add_u64 v[216:217], v[216:217], 0, s[100:101]
	global_load_dword v207, v[216:217], off
	v_lshl_add_u64 v[216:217], v[216:217], 0, s[100:101]
	global_load_dword v208, v[216:217], off
	v_lshl_add_u64 v[216:217], v[216:217], 0, s[100:101]
	global_load_dword v209, v[216:217], off
	v_lshl_add_u64 v[216:217], v[216:217], 0, s[100:101]
	global_load_dword v210, v[216:217], off
	v_lshl_add_u64 v[216:217], v[216:217], 0, s[100:101]
	global_load_dword v211, v[216:217], off
	v_lshl_add_u64 v[216:217], v[216:217], 0, s[100:101]
	global_load_dword v212, v[216:217], off
	v_lshl_add_u64 v[216:217], v[216:217], 0, s[100:101]
	global_load_dword v213, v[216:217], off
	v_lshl_add_u64 v[216:217], v[216:217], 0, s[100:101]
	s_or_b64 exec, exec, s[98:99]
	s_waitcnt vmcnt(60)
	v_readlane_b32 s98, v214, 0
	v_readlane_b32 s99, v214, 1
	v_readlane_b32 s100, v214, 2
	v_readlane_b32 s101, v214, 3
	v_mul_f32_e32 v150, s98, v150
	v_mul_f32_e32 v151, s99, v151
	v_mul_f32_e32 v152, s100, v152
	v_mul_f32_e32 v153, s101, v153
	ds_write_b32 v68, v150
	ds_write_b32 v68, v151 offset:260
	ds_write_b32 v68, v152 offset:520
	ds_write_b32 v68, v153 offset:780
	s_waitcnt vmcnt(56)
	v_readlane_b32 s98, v214, 4
	v_readlane_b32 s99, v214, 5
	v_readlane_b32 s100, v214, 6
	v_readlane_b32 s101, v214, 7
	v_mul_f32_e32 v154, s98, v154
	v_mul_f32_e32 v155, s99, v155
	v_mul_f32_e32 v156, s100, v156
	v_mul_f32_e32 v157, s101, v157
	ds_write_b32 v68, v154 offset:1040
	ds_write_b32 v68, v155 offset:1300
	ds_write_b32 v68, v156 offset:1560
	ds_write_b32 v68, v157 offset:1820
	s_waitcnt vmcnt(52)
	v_readlane_b32 s98, v214, 8
	v_readlane_b32 s99, v214, 9
	v_readlane_b32 s100, v214, 10
	v_readlane_b32 s101, v214, 11
	v_mul_f32_e32 v158, s98, v158
	v_mul_f32_e32 v159, s99, v159
	v_mul_f32_e32 v160, s100, v160
	v_mul_f32_e32 v161, s101, v161
	ds_write_b32 v68, v158 offset:2080
	ds_write_b32 v68, v159 offset:2340
	ds_write_b32 v68, v160 offset:2600
	ds_write_b32 v68, v161 offset:2860
	s_waitcnt vmcnt(48)
	v_readlane_b32 s98, v214, 12
	v_readlane_b32 s99, v214, 13
	v_readlane_b32 s100, v214, 14
	v_readlane_b32 s101, v214, 15
	v_mul_f32_e32 v162, s98, v162
	v_mul_f32_e32 v163, s99, v163
	v_mul_f32_e32 v164, s100, v164
	v_mul_f32_e32 v165, s101, v165
	ds_write_b32 v68, v162 offset:3120
	ds_write_b32 v68, v163 offset:3380
	ds_write_b32 v68, v164 offset:3640
	ds_write_b32 v68, v165 offset:3900
	s_waitcnt vmcnt(44)
	v_readlane_b32 s98, v214, 16
	v_readlane_b32 s99, v214, 17
	v_readlane_b32 s100, v214, 18
	v_readlane_b32 s101, v214, 19
	v_mul_f32_e32 v166, s98, v166
	v_mul_f32_e32 v167, s99, v167
	v_mul_f32_e32 v168, s100, v168
	v_mul_f32_e32 v169, s101, v169
	ds_write_b32 v68, v166 offset:4160
	ds_write_b32 v68, v167 offset:4420
	ds_write_b32 v68, v168 offset:4680
	ds_write_b32 v68, v169 offset:4940
	s_waitcnt vmcnt(40)
; #define LAS __attribute__((address_space(3)))
; __device__ __forceinline__ unsigned pk2(float lo, float hi) { pk_f32x2_t v = {lo, hi}; pk_bf16x2_t b = __builtin_convertvector(v, pk_bf16x2_t); return __builtin_bit_cast(unsigned, b); }
; #define LDS_WAIT() asm volatile("s_waitcnt lgkmcnt(0)" ::: "memory")
; template <int MAP> __device__ __forceinline__ void transpose_item(const float* W, int K, int N, const float* gk, bf16_t* WT, LAS float* scr, int item, int lane) {
;     ...
; #pragma unroll
;     for (int i = 0; i < 64; ++i) { float v = okn ? W[(size_t)(k0 + i) * N + nn] : 0.f; if (gk) v *= gk[k0 + i]; scr[i * 65 + lane] = v; }
;     LDS_WAIT();
;     const int c = lane & 7;
; #pragma unroll
;     for (int j = 0; j < 8; ++j) { const int n = (lane >> 3) + 8 * j; const LAS float* s = scr + (8 * c) * 65 + n;
;         if (n0 + n < N) { u32x4 o; o.x = pk2(s[0 * 65], s[1 * 65]); o.y = pk2(s[2 * 65], s[3 * 65]); o.z = pk2(s[4 * 65], s[5 * 65]); o.w = pk2(s[6 * 65], s[7 * 65]);
;             if (MAP == 4) { const int nn2 = n0 + n, kk2 = k0 + 8 * c; *(u32x4*)(WT + ((size_t)(((nn2 >> 5) * (K >> 4) + (kk2 >> 4)) * 64 + ((kk2 >> 3) & 1) * 32 + (nn2 & 31)) * 8)) = o; }
;             else *(u32x4*)(WT + (size_t)dst_row<MAP>(n0 + n) * K + k0 + 8 * c) = o; } }
	v_readlane_b32 s98, v214, 20
	v_readlane_b32 s99, v214, 21
	v_readlane_b32 s100, v214, 22
	v_readlane_b32 s101, v214, 23
	v_mul_f32_e32 v170, s98, v170
	v_mul_f32_e32 v171, s99, v171
	v_mul_f32_e32 v172, s100, v172
	v_mul_f32_e32 v173, s101, v173
	ds_write_b32 v68, v170 offset:5200
	ds_write_b32 v68, v171 offset:5460
	ds_write_b32 v68, v172 offset:5720
	ds_write_b32 v68, v173 offset:5980
	s_waitcnt vmcnt(36)
	v_readlane_b32 s98, v214, 24
	v_readlane_b32 s99, v214, 25
	v_readlane_b32 s100, v214, 26
	v_readlane_b32 s101, v214, 27
	v_mul_f32_e32 v174, s98, v174
	v_mul_f32_e32 v175, s99, v175
	v_mul_f32_e32 v176, s100, v176
	v_mul_f32_e32 v177, s101, v177
	ds_write_b32 v68, v174 offset:6240
	ds_write_b32 v68, v175 offset:6500
	ds_write_b32 v68, v176 offset:6760
	ds_write_b32 v68, v177 offset:7020
	s_waitcnt vmcnt(32)
	v_readlane_b32 s98, v214, 28
	v_readlane_b32 s99, v214, 29
	v_readlane_b32 s100, v214, 30
	v_readlane_b32 s101, v214, 31
	v_mul_f32_e32 v178, s98, v178
	v_mul_f32_e32 v179, s99, v179
	v_mul_f32_e32 v180, s100, v180
	v_mul_f32_e32 v181, s101, v181
	ds_write_b32 v68, v178 offset:7280
	ds_write_b32 v68, v179 offset:7540
	ds_write_b32 v68, v180 offset:7800
	ds_write_b32 v68, v181 offset:8060
	s_waitcnt vmcnt(28)
	v_readlane_b32 s98, v214, 32
	v_readlane_b32 s99, v214, 33
	v_readlane_b32 s100, v214, 34
	v_readlane_b32 s101, v214, 35
	v_mul_f32_e32 v182, s98, v182
	v_mul_f32_e32 v183, s99, v183
	v_mul_f32_e32 v184, s100, v184
	v_mul_f32_e32 v185, s101, v185
	ds_write_b32 v68, v182 offset:8320
	ds_write_b32 v68, v183 offset:8580
	ds_write_b32 v68, v184 offset:8840
	ds_write_b32 v68, v185 offset:9100
	s_waitcnt vmcnt(24)
	v_readlane_b32 s98, v214, 36
	v_readlane_b32 s99, v214, 37
	v_readlane_b32 s100, v214, 38
	v_readlane_b32 s101, v214, 39
	v_mul_f32_e32 v186, s98, v186
	v_mul_f32_e32 v187, s99, v187
	v_mul_f32_e32 v188, s100, v188
	v_mul_f32_e32 v189, s101, v189
	ds_write_b32 v68, v186 offset:9360
	ds_write_b32 v68, v187 offset:9620
	ds_write_b32 v68, v188 offset:9880
	ds_write_b32 v68, v189 offset:10140
	s_waitcnt vmcnt(20)
	v_readlane_b32 s98, v214, 40
	v_readlane_b32 s99, v214, 41
	v_readlane_b32 s100, v214, 42
	v_readlane_b32 s101, v214, 43
	v_mul_f32_e32 v190, s98, v190
	v_mul_f32_e32 v191, s99, v191
	v_mul_f32_e32 v192, s100, v192
	v_mul_f32_e32 v193, s101, v193
	ds_write_b32 v68, v190 offset:10400
	ds_write_b32 v68, v191 offset:10660
	ds_write_b32 v68, v192 offset:10920
	ds_write_b32 v68, v193 offset:11180
	s_waitcnt vmcnt(16)
	v_readlane_b32 s98, v214, 44
	v_readlane_b32 s99, v214, 45
	v_readlane_b32 s100, v214, 46
	v_readlane_b32 s101, v214, 47
	v_mul_f32_e32 v194, s98, v194
	v_mul_f32_e32 v195, s99, v195
	v_mul_f32_e32 v196, s100, v196
	v_mul_f32_e32 v197, s101, v197
	ds_write_b32 v68, v194 offset:11440
	ds_write_b32 v68, v195 offset:11700
	ds_write_b32 v68, v196 offset:11960
	ds_write_b32 v68, v197 offset:12220
	s_waitcnt vmcnt(12)
	v_readlane_b32 s98, v214, 48
	v_readlane_b32 s99, v214, 49
	v_readlane_b32 s100, v214, 50
	v_readlane_b32 s101, v214, 51
	v_mul_f32_e32 v198, s98, v198
	v_mul_f32_e32 v199, s99, v199
	v_mul_f32_e32 v200, s100, v200
	v_mul_f32_e32 v201, s101, v201
	ds_write_b32 v68, v198 offset:12480
	ds_write_b32 v68, v199 offset:12740
	ds_write_b32 v68, v200 offset:13000
	ds_write_b32 v68, v201 offset:13260
	s_waitcnt vmcnt(8)
	v_readlane_b32 s98, v214, 52
	v_readlane_b32 s99, v214, 53
	v_readlane_b32 s100, v214, 54
	v_readlane_b32 s101, v214, 55
	v_mul_f32_e32 v202, s98, v202
	v_mul_f32_e32 v203, s99, v203
	v_mul_f32_e32 v204, s100, v204
	v_mul_f32_e32 v205, s101, v205
	ds_write_b32 v68, v202 offset:13520
	ds_write_b32 v68, v203 offset:13780
	ds_write_b32 v68, v204 offset:14040
	ds_write_b32 v68, v205 offset:14300
	s_waitcnt vmcnt(4)
	v_readlane_b32 s98, v214, 56
	v_readlane_b32 s99, v214, 57
	v_readlane_b32 s100, v214, 58
	v_readlane_b32 s101, v214, 59
	v_mul_f32_e32 v206, s98, v206
	v_mul_f32_e32 v207, s99, v207
	v_mul_f32_e32 v208, s100, v208
	v_mul_f32_e32 v209, s101, v209
	ds_write_b32 v68, v206 offset:14560
	ds_write_b32 v68, v207 offset:14820
	ds_write_b32 v68, v208 offset:15080
	ds_write_b32 v68, v209 offset:15340
	s_waitcnt vmcnt(0)
	v_readlane_b32 s98, v214, 60
	v_readlane_b32 s99, v214, 61
	v_readlane_b32 s100, v214, 62
	v_readlane_b32 s101, v214, 63
	v_mul_f32_e32 v210, s98, v210
	v_mul_f32_e32 v211, s99, v211
	v_mul_f32_e32 v212, s100, v212
	v_mul_f32_e32 v213, s101, v213
	ds_write_b32 v68, v210 offset:15600
	ds_write_b32 v68, v211 offset:15860
	ds_write_b32 v68, v212 offset:16120
	ds_write_b32 v68, v213 offset:16380
	s_lshl_b64 s[4:5], s[8:9], 1
	s_waitcnt lgkmcnt(0)
	s_add_u32 s4, s97, s4
	s_addc_u32 s5, s71, s5
	v_or_b32_e32 v4, s14, v69
	v_lshl_add_u64 v[2:3], s[4:5], 0, v[10:11]
	v_cmp_gt_i32_e32 vcc, s93, v4
	s_and_saveexec_b64 s[4:5], vcc
	s_cbranch_execz .LBB0_555
	ds_read2_b32 v[6:7], v71 offset1:65
	ds_read2_b32 v[8:9], v71 offset0:130 offset1:195
	ds_read2_b32 v[12:13], v96 offset0:4 offset1:69
	ds_read2_b32 v[14:15], v96 offset0:134 offset1:199
	v_cmp_lt_i32_e32 vcc, s94, v4
	s_and_saveexec_b64 s[6:7], vcc
	s_cbranch_execz .LBB0_554
	v_cmp_lt_u32_e32 vcc, s95, v4
	s_and_saveexec_b64 s[8:9], vcc
	s_xor_b64 s[8:9], exec, s[8:9]
	v_add_u32_e32 v4, -12, v4
	s_andn2_saveexec_b64 s[8:9], s[8:9]
	v_add_u32_e32 v4, 0x900, v4
	s_or_b64 exec, exec, s[8:9]

; #define LAS __attribute__((address_space(3)))
; __global__ void __launch_bounds__(512, 2) fwd_kernel(Params p) {
;     extern __shared__ __attribute__((aligned(16))) unsigned char lds_raw[];
;     cg::grid_group grid = cg::this_grid();
;     LAS unsigned char* lds = (LAS unsigned char*)lds_raw;
	.amdhsa_kernel _Z10fwd_kernel6Params
		.amdhsa_group_segment_fixed_size 0
		.amdhsa_private_segment_fixed_size 0
		.amdhsa_kernarg_size 456
		.amdhsa_user_sgpr_count 2
		.amdhsa_user_sgpr_dispatch_ptr 0
		.amdhsa_user_sgpr_queue_ptr 0
		.amdhsa_user_sgpr_kernarg_segment_ptr 1
		.amdhsa_user_sgpr_dispatch_id 0
		.amdhsa_user_sgpr_kernarg_preload_length 0
		.amdhsa_user_sgpr_kernarg_preload_offset 0
		.amdhsa_user_sgpr_private_segment_size 0
		.amdhsa_uses_dynamic_stack 0
		.amdhsa_enable_private_segment 0
		.amdhsa_system_sgpr_workgroup_id_x 1
		.amdhsa_system_sgpr_workgroup_id_y 0
		.amdhsa_system_sgpr_workgroup_id_z 0
		.amdhsa_system_sgpr_workgroup_info 0
		.amdhsa_system_vgpr_workitem_id 2
		.amdhsa_next_free_vgpr 256
		.amdhsa_next_free_sgpr 102
		.amdhsa_accum_offset 256
		.amdhsa_reserve_vcc 1
		.amdhsa_float_round_mode_32 0
		.amdhsa_float_round_mode_16_64 0
		.amdhsa_float_denorm_mode_32 3
		.amdhsa_float_denorm_mode_16_64 3
		.amdhsa_dx10_clamp 1
		.amdhsa_ieee_mode 1
		.amdhsa_fp16_overflow 0
		.amdhsa_tg_split 0
		.amdhsa_exception_fp_ieee_invalid_op 0
		.amdhsa_exception_fp_denorm_src 0
		.amdhsa_exception_fp_ieee_div_zero 0
		.amdhsa_exception_fp_ieee_overflow 0
		.amdhsa_exception_fp_ieee_underflow 0
		.amdhsa_exception_fp_ieee_inexact 0
		.amdhsa_exception_int_div_zero 0
	.end_amdhsa_kernel

; #define LAS __attribute__((address_space(3)))
; __global__ void __launch_bounds__(512, 2) fwd_kernel(Params p) {
;     extern __shared__ __attribute__((aligned(16))) unsigned char lds_raw[];
;     cg::grid_group grid = cg::this_grid();
;     LAS unsigned char* lds = (LAS unsigned char*)lds_raw;
amdhsa.kernels:
  - .agpr_count:     0
    .args:
      - .offset:         0
        .size:           200
        .value_kind:     by_value
      - .offset:         200
        .size:           4
        .value_kind:     hidden_block_count_x
      - .offset:         204
        .size:           4
        .value_kind:     hidden_block_count_y
      - .offset:         208
        .size:           4
        .value_kind:     hidden_block_count_z
      - .offset:         212
        .size:           2
        .value_kind:     hidden_group_size_x
      - .offset:         214
        .size:           2
        .value_kind:     hidden_group_size_y
      - .offset:         216
        .size:           2
        .value_kind:     hidden_group_size_z
      - .offset:         218
        .size:           2
        .value_kind:     hidden_remainder_x
      - .offset:         220
        .size:           2
        .value_kind:     hidden_remainder_y
      - .offset:         222
        .size:           2
        .value_kind:     hidden_remainder_z
      - .offset:         240
        .size:           8
        .value_kind:     hidden_global_offset_x
      - .offset:         248
        .size:           8
        .value_kind:     hidden_global_offset_y
      - .offset:         256
        .size:           8
        .value_kind:     hidden_global_offset_z
      - .offset:         264
        .size:           2
        .value_kind:     hidden_grid_dims
      - .offset:         288
        .size:           8
        .value_kind:     hidden_multigrid_sync_arg
      - .offset:         320
        .size:           4
        .value_kind:     hidden_dynamic_lds_size
    .group_segment_fixed_size: 0
    .kernarg_segment_align: 8
    .kernarg_segment_size: 456
    .language:       OpenCL C
    .language_version:
      - 2
      - 0
    .max_flat_workgroup_size: 512
    .name:           _Z10fwd_kernel6Params
    .private_segment_fixed_size: 0
    .sgpr_count:     108
    .sgpr_spill_count: 216
    .symbol:         _Z10fwd_kernel6Params.kd
    .uniform_work_group_size: 1
    .uses_dynamic_stack: false
    .vgpr_count:     256
    .vgpr_spill_count: 0
    .wavefront_size: 64
